# k7 plus: MLA row-sum zero-adds folded, dilated-attention QK K-fragment reads 4 pairs deep
# speedup vs baseline: 1.0062x; 1.0062x over previous
; #define LAS __attribute__((address_space(3)))
; #define MFMA32(a, b, c) __builtin_amdgcn_mfma_f32_32x32x16_bf16(a, b, c, 0, 0, 0)
; __device__ __forceinline__ float xhalf_max(float v) { auto rr = __builtin_amdgcn_permlane32_swap(__float_as_uint(v), __float_as_uint(v), false, false); return fmaxf(__uint_as_float(rr[0]), __uint_as_float(rr[1])); }
; __device__ __forceinline__ float max3(float a, float b, float c) { float r; asm("v_max3_f32 %0, %1, %2, %3" : "=v"(r) : "v"(a), "v"(b), "v"(c)); return r; }
; __device__ __forceinline__ void attn_dil_phase(LAS unsigned char* lds, const bf16_t* QKV, const float* BT, bf16_t* OG, float* LSE, int nseq, int log2S, int G, int bx) {
;     ...
;             if (t >= wt0 && t <= wt0 + 2 && (fk0 >> log2L) == myblk) {
;                 const LAS unsigned char* Kb = lds + cur * KBUF;
;                 f32x16 s0 = {}, s1 = {};
; #pragma unroll
;                 for (int ks = 0; ks < 8; ++ks) {
;                     const bf16x8 a0 = *(const LAS bf16x8*)(Kb + r32 * 272 + ks * 32 + hi * 16), a1 = *(const LAS bf16x8*)(Kb + (32 + r32) * 272 + ks * 32 + hi * 16);
;                     s0 = MFMA32(a0, qf[ks], s0); s1 = MFMA32(a1, qf[ks], s1);
;                 }
;                 const LAS float* tb = tab + tbase + 64 * t;
; #pragma unroll
;                 for (int r = 0; r < 16; ++r) { s0[r] += tb[(r & 3) + 8 * (r >> 2)]; s1[r] += tb[32 + (r & 3) + 8 * (r >> 2)]; }
;                 float pa = max3(s0[0], s0[1], s0[2]), pc = max3(s1[0], s1[1], s1[2]);
; #pragma unroll
;                 for (int r = 3; r < 15; r += 2) { pa = max3(pa, s0[r], s0[r + 1]); pc = max3(pc, s1[r], s1[r + 1]); }
;                 float pmax = max3(pa, pc, fmaxf(s0[15], s1[15]));
;                 pmax = xhalf_max(pmax);
;                 if (__any(pmax > m + 8.f)) {
.LBB0_296:
	s_and_b32 s29, s31, 1
	s_cmp_ge_i32 s30, s62
	s_cselect_b64 s[36:37], -1, 0
	s_cmp_le_i32 s30, s63
	s_cselect_b64 s[50:51], -1, 0
	s_and_b64 s[36:37], s[36:37], s[50:51]
	s_ashr_i32 s30, s17, s8
	s_cmp_eq_u32 s30, s15
	s_cselect_b64 s[50:51], -1, 0
	s_and_b64 s[36:37], s[36:37], s[50:51]
	s_andn2_b64 vcc, exec, s[36:37]
	s_cbranch_vccnz .LBB0_300
	s_mul_i32 s30, s29, 0x4400
	v_add_u32_e32 v0, s30, v225
	ds_read_b128 v[228:231], v0
	ds_read_b128 v[232:235], v0 offset:8704
	ds_read_b128 v[236:239], v0 offset:32
	ds_read_b128 v[240:243], v0 offset:8736
	ds_read_b128 v[244:247], v0 offset:64
	ds_read_b128 v[10:13], v0 offset:8768
	ds_read_b128 v[2:5], v0 offset:96
	ds_read_b128 v[6:9], v0 offset:8800
	s_waitcnt lgkmcnt(7)
	v_mfma_f32_32x32x16_bf16 v[80:95], v[228:231], v[160:163], 0
	s_waitcnt lgkmcnt(6)
	v_mfma_f32_32x32x16_bf16 v[96:111], v[232:235], v[160:163], 0
	ds_read_b128 v[228:231], v0 offset:128
	ds_read_b128 v[232:235], v0 offset:8832
	s_waitcnt lgkmcnt(7)
	v_mfma_f32_32x32x16_bf16 v[80:95], v[236:239], v[164:167], v[80:95]
	s_waitcnt lgkmcnt(6)
	v_mfma_f32_32x32x16_bf16 v[96:111], v[240:243], v[164:167], v[96:111]
	ds_read_b128 v[236:239], v0 offset:160
	ds_read_b128 v[240:243], v0 offset:8864
	s_waitcnt lgkmcnt(7)
	v_mfma_f32_32x32x16_bf16 v[80:95], v[244:247], v[168:171], v[80:95]
	s_waitcnt lgkmcnt(6)
	v_mfma_f32_32x32x16_bf16 v[96:111], v[10:13], v[168:171], v[96:111]
	ds_read_b128 v[244:247], v0 offset:192
	ds_read_b128 v[10:13], v0 offset:8896
	s_waitcnt lgkmcnt(7)
	v_mfma_f32_32x32x16_bf16 v[80:95], v[2:5], v[172:175], v[80:95]
	s_waitcnt lgkmcnt(6)
	v_mfma_f32_32x32x16_bf16 v[96:111], v[6:9], v[172:175], v[96:111]
	ds_read_b128 v[2:5], v0 offset:224
	ds_read_b128 v[6:9], v0 offset:8928
	s_waitcnt lgkmcnt(7)
	v_mfma_f32_32x32x16_bf16 v[80:95], v[228:231], v[176:179], v[80:95]
	s_waitcnt lgkmcnt(6)
	v_mfma_f32_32x32x16_bf16 v[96:111], v[232:235], v[176:179], v[96:111]
	s_waitcnt lgkmcnt(5)
	v_mfma_f32_32x32x16_bf16 v[80:95], v[236:239], v[180:183], v[80:95]
	s_waitcnt lgkmcnt(4)
	v_mfma_f32_32x32x16_bf16 v[96:111], v[240:243], v[180:183], v[96:111]
	s_waitcnt lgkmcnt(3)
	v_mfma_f32_32x32x16_bf16 v[80:95], v[244:247], v[184:187], v[80:95]
	s_waitcnt lgkmcnt(2)
	v_mfma_f32_32x32x16_bf16 v[96:111], v[10:13], v[184:187], v[96:111]
	ds_read2_b32 v[10:11], v207 offset0:34 offset1:35
	ds_read2_b32 v[14:15], v207 offset0:40 offset1:41
	ds_read2_b32 v[12:13], v207 offset0:8 offset1:9
	s_waitcnt lgkmcnt(4)
	v_mfma_f32_32x32x16_bf16 v[80:95], v[2:5], v[188:191], v[80:95]
	ds_read2_b32 v[4:5], v207 offset1:1
	s_waitcnt lgkmcnt(4)
	v_mfma_f32_32x32x16_bf16 v[96:111], v[6:9], v[188:191], v[96:111]
	ds_read2_b32 v[6:7], v207 offset0:32 offset1:33
	ds_read2_b32 v[8:9], v207 offset0:2 offset1:3
	s_waitcnt lgkmcnt(2)
	s_nop 5
	v_add_f32_e32 v3, v80, v4
	v_add_f32_e32 v2, v81, v5
	ds_read2_b32 v[80:81], v207 offset0:42 offset1:43
	s_waitcnt lgkmcnt(2)
	v_add_f32_e32 v4, v96, v6
	v_add_f32_e32 v0, v97, v7
	s_waitcnt lgkmcnt(1)
	v_add_f32_e32 v7, v82, v8
	v_add_f32_e32 v6, v83, v9
	ds_read2_b32 v[82:83], v207 offset0:16 offset1:17
	ds_read2_b32 v[96:97], v207 offset0:50 offset1:51
	v_add_f32_e32 v5, v99, v11
	v_add_f32_e32 v11, v84, v12
	v_add_f32_e32 v12, v100, v14
	v_add_f32_e32 v9, v101, v15
	ds_read2_b32 v[14:15], v207 offset0:10 offset1:11
	v_add_f32_e32 v8, v98, v10
	v_add_f32_e32 v10, v85, v13
	ds_read2_b32 v[84:85], v207 offset0:48 offset1:49
	s_waitcnt lgkmcnt(3)
	v_add_f32_e32 v83, v89, v83
	s_waitcnt lgkmcnt(1)
	v_add_f32_e32 v13, v86, v14
	v_add_f32_e32 v14, v103, v81
	v_add_f32_e32 v81, v88, v82
	ds_read2_b32 v[88:89], v207 offset0:18 offset1:19
	v_add_f32_e32 v15, v87, v15
	s_waitcnt lgkmcnt(1)
	v_add_f32_e32 v82, v105, v85
	v_add_f32_e32 v85, v107, v97
	ds_read2_b32 v[98:99], v207 offset0:56 offset1:57
	s_waitcnt lgkmcnt(1)
	v_add_f32_e32 v87, v90, v88
	v_add_f32_e32 v88, v106, v96
	ds_read2_b32 v[96:97], v207 offset0:24 offset1:25
	v_add_f32_e32 v86, v91, v89
	s_waitcnt lgkmcnt(1)
	v_add_f32_e32 v89, v109, v99
	v_add_f32_e32 v80, v102, v80
	v_add_f32_e32 v84, v104, v84
	s_waitcnt lgkmcnt(0)
	v_add_f32_e32 v91, v92, v96
	v_add_f32_e32 v92, v108, v98
	v_add_f32_e32 v90, v93, v97
	ds_read2_b32 v[96:97], v207 offset0:26 offset1:27
	ds_read2_b32 v[98:99], v207 offset0:58 offset1:59
	s_waitcnt lgkmcnt(1)
	v_add_f32_e32 v93, v94, v96
	s_waitcnt lgkmcnt(0)
	v_add_f32_e32 v96, v110, v98
	v_add_f32_e32 v95, v95, v97
	v_max3_f32 v97, v3, v2, v7
	v_max3_f32 v98, v4, v0, v8
	v_add_f32_e32 v94, v111, v99
	v_max3_f32 v97, v97, v6, v11
	v_max3_f32 v98, v98, v5, v12
	v_max_f32_e32 v99, v95, v94
	v_max3_f32 v97, v97, v10, v13
	v_max3_f32 v98, v98, v9, v80
	s_nop 0
	v_max3_f32 v97, v97, v15, v81
	v_max3_f32 v98, v98, v14, v84
	s_nop 0
	v_max3_f32 v97, v97, v83, v87
	v_max3_f32 v98, v98, v82, v88
	s_nop 0
	v_max3_f32 v97, v97, v86, v91
	v_max3_f32 v98, v98, v85, v92
	s_nop 0
	v_max3_f32 v97, v97, v90, v93
	v_max3_f32 v98, v98, v89, v96
	s_nop 0
	v_max3_f32 v97, v97, v98, v99
	s_nop 0
	v_mov_b32_e32 v98, v97
	s_nop 1
	v_permlane32_swap_b32_e32 v97, v98
	v_max_f32_e32 v98, v98, v98
	v_max_f32_e32 v97, v97, v97
	v_max_f32_e32 v97, v97, v98
	v_add_f32_e32 v98, 0x41000000, v205
	v_cmp_gt_f32_e32 vcc, v97, v98
	s_cbranch_vccz .LBB0_299
; __device__ __forceinline__ void attn_dil_phase(LAS unsigned char* lds, const bf16_t* QKV, const float* BT, bf16_t* OG, float* LSE, int nseq, int log2S, int G, int bx) {
;     ...
;                 if (__any(pmax > m + 8.f)) {
;                     const float mn = fmaxf(m, pmax), alpha = __builtin_amdgcn_exp2f(m - mn);
;                     m = mn; l *= alpha;
; #pragma unroll
;                     for (int d = 0; d < 4; ++d)
; #pragma unroll
;                         for (int r = 0; r < 16; ++r) o[d][r] *= alpha;
;                 }
	v_max_f32_e32 v97, v97, v97
	v_max_f32_e32 v98, v205, v205
	v_max_f32_e32 v97, v98, v97
	v_sub_f32_e32 v98, v205, v97
	v_exp_f32_e32 v98, v98
	v_mov_b32_e32 v205, v97
	v_pk_mul_f32 v[78:79], v[78:79], v[98:99] op_sel_hi:[1,0]
	v_pk_mul_f32 v[76:77], v[76:77], v[98:99] op_sel_hi:[1,0]
	v_pk_mul_f32 v[74:75], v[74:75], v[98:99] op_sel_hi:[1,0]
	v_pk_mul_f32 v[72:73], v[72:73], v[98:99] op_sel_hi:[1,0]
	v_pk_mul_f32 v[70:71], v[70:71], v[98:99] op_sel_hi:[1,0]
	v_pk_mul_f32 v[68:69], v[68:69], v[98:99] op_sel_hi:[1,0]
	v_pk_mul_f32 v[66:67], v[66:67], v[98:99] op_sel_hi:[1,0]
	v_pk_mul_f32 v[64:65], v[64:65], v[98:99] op_sel_hi:[1,0]
	v_pk_mul_f32 v[62:63], v[62:63], v[98:99] op_sel_hi:[1,0]
	v_pk_mul_f32 v[60:61], v[60:61], v[98:99] op_sel_hi:[1,0]
	v_pk_mul_f32 v[58:59], v[58:59], v[98:99] op_sel_hi:[1,0]
	v_pk_mul_f32 v[56:57], v[56:57], v[98:99] op_sel_hi:[1,0]
	v_pk_mul_f32 v[54:55], v[54:55], v[98:99] op_sel_hi:[1,0]
	v_pk_mul_f32 v[52:53], v[52:53], v[98:99] op_sel_hi:[1,0]
	v_pk_mul_f32 v[50:51], v[50:51], v[98:99] op_sel_hi:[1,0]
	v_pk_mul_f32 v[48:49], v[48:49], v[98:99] op_sel_hi:[1,0]
	v_pk_mul_f32 v[46:47], v[46:47], v[98:99] op_sel_hi:[1,0]
	v_pk_mul_f32 v[44:45], v[44:45], v[98:99] op_sel_hi:[1,0]
	v_pk_mul_f32 v[42:43], v[42:43], v[98:99] op_sel_hi:[1,0]
	v_pk_mul_f32 v[40:41], v[40:41], v[98:99] op_sel_hi:[1,0]
	v_pk_mul_f32 v[38:39], v[38:39], v[98:99] op_sel_hi:[1,0]
	v_pk_mul_f32 v[36:37], v[36:37], v[98:99] op_sel_hi:[1,0]
	v_pk_mul_f32 v[34:35], v[34:35], v[98:99] op_sel_hi:[1,0]
	v_pk_mul_f32 v[32:33], v[32:33], v[98:99] op_sel_hi:[1,0]
	v_pk_mul_f32 v[30:31], v[30:31], v[98:99] op_sel_hi:[1,0]
	v_pk_mul_f32 v[28:29], v[28:29], v[98:99] op_sel_hi:[1,0]
	v_pk_mul_f32 v[26:27], v[26:27], v[98:99] op_sel_hi:[1,0]
	v_pk_mul_f32 v[24:25], v[24:25], v[98:99] op_sel_hi:[1,0]
	v_pk_mul_f32 v[22:23], v[22:23], v[98:99] op_sel_hi:[1,0]
	v_pk_mul_f32 v[20:21], v[20:21], v[98:99] op_sel_hi:[1,0]
	v_pk_mul_f32 v[18:19], v[18:19], v[98:99] op_sel_hi:[1,0]
	v_pk_mul_f32 v[16:17], v[16:17], v[98:99] op_sel_hi:[1,0]
	v_mul_f32_e32 v227, v227, v98

.LBB0_785:
	v_exp_f32_e32 v148, v52
	s_nop 0
	v_exp_f32_e32 v150, v36
	v_exp_f32_e32 v149, v53
	v_exp_f32_e32 v151, v37
	v_exp_f32_e32 v54, v54
	v_exp_f32_e32 v152, v38
	v_exp_f32_e32 v55, v55
	v_exp_f32_e32 v153, v39
	v_exp_f32_e32 v38, v56
	v_exp_f32_e32 v56, v40
	v_exp_f32_e32 v39, v57
	v_exp_f32_e32 v57, v41
	v_exp_f32_e32 v40, v58
	v_exp_f32_e32 v58, v42
	v_exp_f32_e32 v41, v59
	v_exp_f32_e32 v59, v43
	v_exp_f32_e32 v42, v60
	v_exp_f32_e32 v60, v44
	v_exp_f32_e32 v43, v61
	v_exp_f32_e32 v61, v45
	v_exp_f32_e32 v44, v62
	v_exp_f32_e32 v62, v46
	v_exp_f32_e32 v45, v63
	v_exp_f32_e32 v63, v47
	v_exp_f32_e32 v46, v64
	v_exp_f32_e32 v64, v48
	v_exp_f32_e32 v47, v65
	v_exp_f32_e32 v65, v49
	v_exp_f32_e32 v48, v66
	v_exp_f32_e32 v66, v50
	v_exp_f32_e32 v49, v67
	v_exp_f32_e32 v67, v51
	v_pk_add_f32 v[36:37], v[38:39], v[148:149]
	v_pk_add_f32 v[50:51], v[40:41], v[54:55]
	v_pk_add_f32 v[52:53], v[56:57], v[150:151]
	v_pk_add_f32 v[154:155], v[58:59], v[152:153]
	v_pk_add_f32 v[36:37], v[42:43], v[36:37]
	v_pk_add_f32 v[50:51], v[44:45], v[50:51]
	v_pk_add_f32 v[52:53], v[60:61], v[52:53]
	v_pk_add_f32 v[154:155], v[62:63], v[154:155]
	v_pk_add_f32 v[36:37], v[46:47], v[36:37]
	v_pk_add_f32 v[50:51], v[48:49], v[50:51]
	v_pk_add_f32 v[52:53], v[64:65], v[52:53]
	v_pk_add_f32 v[154:155], v[66:67], v[154:155]
	v_pk_add_f32 v[36:37], v[50:51], v[36:37]
	v_pk_add_f32 v[50:51], v[154:155], v[52:53]
	s_mov_b64 s[16:17], -1
	v_pk_add_f32 v[36:37], v[50:51], v[36:37]
	s_and_b64 vcc, exec, s[18:19]
	v_add_f32_e32 v52, v36, v37
	v_cvt_pk_bf16_f32 v36, v148, v149
	v_cvt_pk_bf16_f32 v37, v54, v55
	v_cvt_pk_bf16_f32 v38, v38, v39
	v_cvt_pk_bf16_f32 v39, v40, v41
	v_cvt_pk_bf16_f32 v40, v42, v43
	v_cvt_pk_bf16_f32 v41, v44, v45
	v_cvt_pk_bf16_f32 v42, v46, v47
	v_cvt_pk_bf16_f32 v43, v48, v49
	v_cvt_pk_bf16_f32 v44, v150, v151
	v_cvt_pk_bf16_f32 v45, v152, v153
	v_cvt_pk_bf16_f32 v46, v56, v57
	v_cvt_pk_bf16_f32 v47, v58, v59
	v_cvt_pk_bf16_f32 v48, v60, v61
	v_cvt_pk_bf16_f32 v49, v62, v63
	v_cvt_pk_bf16_f32 v50, v64, v65
	v_cvt_pk_bf16_f32 v51, v66, v67
	s_cbranch_vccnz .LBB0_789
	v_cmp_ngt_f32_e32 vcc, s67, v52
	s_cbranch_vccz .LBB0_788
	ds_read_b128 v[52:55], v234 offset:6656
	ds_read_b128 v[36:39], v234
	ds_read_b128 v[148:151], v234 offset:32
	ds_read_b128 v[152:155], v234 offset:6688
	s_waitcnt lgkmcnt(3)
	v_mfma_f32_32x32x16_bf16 v[52:67], v[52:55], v[68:71], 0
	s_waitcnt lgkmcnt(2)
	v_mfma_f32_32x32x16_bf16 v[36:51], v[36:39], v[68:71], 0
	s_waitcnt lgkmcnt(1)
	v_mfma_f32_32x32x16_bf16 v[36:51], v[148:151], v[72:75], v[36:51]
	s_waitcnt lgkmcnt(0)
	v_mfma_f32_32x32x16_bf16 v[52:67], v[152:155], v[72:75], v[52:67]
	ds_read_b128 v[148:151], v234 offset:64
	ds_read_b128 v[152:155], v234 offset:6720
	s_waitcnt lgkmcnt(1)
	v_mfma_f32_32x32x16_bf16 v[36:51], v[148:151], v[76:79], v[36:51]
	s_waitcnt lgkmcnt(0)
	v_mfma_f32_32x32x16_bf16 v[52:67], v[152:155], v[76:79], v[52:67]
	ds_read_b128 v[148:151], v234 offset:96
	ds_read_b128 v[152:155], v234 offset:6752
	s_waitcnt lgkmcnt(1)
	v_mfma_f32_32x32x16_bf16 v[36:51], v[148:151], v[80:83], v[36:51]
	s_waitcnt lgkmcnt(0)
	v_mfma_f32_32x32x16_bf16 v[52:67], v[152:155], v[80:83], v[52:67]
	ds_read_b128 v[148:151], v234 offset:128
	ds_read_b128 v[152:155], v234 offset:6784
	s_waitcnt lgkmcnt(1)
	v_mfma_f32_32x32x16_bf16 v[36:51], v[148:151], v[84:87], v[36:51]
	s_waitcnt lgkmcnt(0)
	v_mfma_f32_32x32x16_bf16 v[52:67], v[152:155], v[84:87], v[52:67]
	ds_read_b128 v[148:151], v234 offset:160
	ds_read_b128 v[152:155], v234 offset:6816
	s_waitcnt lgkmcnt(1)
	v_mfma_f32_32x32x16_bf16 v[36:51], v[148:151], v[88:91], v[36:51]
	v_max3_f32 v148, v36, v37, v38
	s_nop 0
	v_max3_f32 v148, v148, v39, v40
	s_nop 0
	v_max3_f32 v148, v148, v41, v42
	s_nop 9
	v_max_f32_e32 v151, v51, v51
	s_waitcnt lgkmcnt(0)
	v_mfma_f32_32x32x16_bf16 v[52:67], v[152:155], v[88:91], v[52:67]
	v_max3_f32 v149, v52, v53, v54
	v_max3_f32 v148, v148, v43, v44
	s_nop 0
	v_max3_f32 v149, v149, v55, v56
	v_max3_f32 v148, v148, v45, v46
	s_nop 10
	v_max_f32_e32 v150, v67, v67
	v_max3_f32 v149, v149, v57, v58
	v_max3_f32 v148, v148, v47, v48
	v_max_f32_e32 v150, v151, v150
	v_max3_f32 v149, v149, v59, v60
	v_max3_f32 v148, v148, v49, v50
	s_nop 0
	v_max3_f32 v149, v149, v61, v62
	s_nop 0
	v_max3_f32 v149, v149, v63, v64
	s_nop 0
	v_max3_f32 v149, v149, v65, v66
	s_nop 0
	v_max3_f32 v148, v148, v149, v150
	s_nop 0
	v_mov_b32_e32 v149, v148
	s_nop 1
	v_permlane32_swap_b32_e32 v148, v149
	v_max3_f32 v158, v167, v148, v149
	v_sub_f32_e32 v36, v36, v158
	v_sub_f32_e32 v52, v52, v158
	v_sub_f32_e32 v37, v37, v158
	v_sub_f32_e32 v53, v53, v158
	v_sub_f32_e32 v38, v38, v158
	v_sub_f32_e32 v54, v54, v158
	v_sub_f32_e32 v39, v39, v158
	v_sub_f32_e32 v55, v55, v158
	v_sub_f32_e32 v40, v40, v158
	v_sub_f32_e32 v56, v56, v158
	v_sub_f32_e32 v41, v41, v158
	v_sub_f32_e32 v57, v57, v158
	v_sub_f32_e32 v42, v42, v158
	v_sub_f32_e32 v58, v58, v158
	v_sub_f32_e32 v43, v43, v158
	v_sub_f32_e32 v59, v59, v158
	v_sub_f32_e32 v149, v44, v158
	v_sub_f32_e32 v150, v45, v158
	v_sub_f32_e32 v151, v46, v158
	v_sub_f32_e32 v152, v47, v158
	v_exp_f32_e32 v36, v36
	v_exp_f32_e32 v44, v52
	v_exp_f32_e32 v37, v37
	v_exp_f32_e32 v45, v53
	v_exp_f32_e32 v38, v38
	v_exp_f32_e32 v46, v54
	v_exp_f32_e32 v39, v39
	v_exp_f32_e32 v47, v55
	v_sub_f32_e32 v60, v60, v158
	v_sub_f32_e32 v61, v61, v158
	v_sub_f32_e32 v62, v62, v158
	v_sub_f32_e32 v63, v63, v158
	v_sub_f32_e32 v153, v48, v158
	v_sub_f32_e32 v154, v49, v158
	v_sub_f32_e32 v155, v50, v158
	v_sub_f32_e32 v157, v51, v158
	v_exp_f32_e32 v40, v40
	v_exp_f32_e32 v48, v56
	v_exp_f32_e32 v41, v41
	v_exp_f32_e32 v49, v57
	v_exp_f32_e32 v42, v42
	v_exp_f32_e32 v50, v58
	v_exp_f32_e32 v43, v43
	v_exp_f32_e32 v51, v59
	v_sub_f32_e32 v64, v64, v158
	v_sub_f32_e32 v65, v65, v158
	v_sub_f32_e32 v156, v66, v158
	v_sub_f32_e32 v159, v67, v158
	v_exp_f32_e32 v54, v149
	v_exp_f32_e32 v56, v60
	v_exp_f32_e32 v55, v150
	v_exp_f32_e32 v57, v61
	v_exp_f32_e32 v58, v151
	v_exp_f32_e32 v60, v62
	v_exp_f32_e32 v59, v152
	v_exp_f32_e32 v61, v63
	v_sub_f32_e32 v148, v167, v158
	v_exp_f32_e32 v62, v153
	v_exp_f32_e32 v64, v64
	v_exp_f32_e32 v63, v154
	v_exp_f32_e32 v65, v65
	v_exp_f32_e32 v66, v155
	v_exp_f32_e32 v150, v156
	v_exp_f32_e32 v67, v157
	v_exp_f32_e32 v151, v159
	v_exp_f32_e32 v148, v148
	v_pk_add_f32 v[52:53], v[36:37], 0 op_sel_hi:[1,0]
	v_pk_add_f32 v[152:153], v[38:39], 0 op_sel_hi:[1,0]
	v_pk_add_f32 v[154:155], v[44:45], 0 op_sel_hi:[1,0]
	v_pk_add_f32 v[156:157], v[46:47], 0 op_sel_hi:[1,0]
	v_pk_add_f32 v[52:53], v[40:41], v[52:53]
	v_pk_add_f32 v[152:153], v[42:43], v[152:153]
	v_pk_add_f32 v[154:155], v[48:49], v[154:155]
	v_pk_add_f32 v[156:157], v[50:51], v[156:157]
	v_pk_add_f32 v[52:53], v[54:55], v[52:53]
	v_pk_add_f32 v[152:153], v[58:59], v[152:153]
	v_pk_add_f32 v[154:155], v[56:57], v[154:155]
	v_pk_add_f32 v[156:157], v[60:61], v[156:157]
	v_pk_add_f32 v[52:53], v[62:63], v[52:53]
	v_pk_add_f32 v[152:153], v[66:67], v[152:153]
	v_pk_add_f32 v[154:155], v[64:65], v[154:155]
	v_pk_add_f32 v[156:157], v[150:151], v[156:157]
	v_pk_mul_f32 v[34:35], v[34:35], v[148:149] op_sel_hi:[1,0]
	v_pk_mul_f32 v[32:33], v[32:33], v[148:149] op_sel_hi:[1,0]
	v_pk_mul_f32 v[30:31], v[30:31], v[148:149] op_sel_hi:[1,0]
	v_pk_mul_f32 v[28:29], v[28:29], v[148:149] op_sel_hi:[1,0]
	v_pk_mul_f32 v[26:27], v[26:27], v[148:149] op_sel_hi:[1,0]
	v_pk_mul_f32 v[24:25], v[24:25], v[148:149] op_sel_hi:[1,0]
	v_pk_mul_f32 v[22:23], v[22:23], v[148:149] op_sel_hi:[1,0]
	v_pk_mul_f32 v[20:21], v[20:21], v[148:149] op_sel_hi:[1,0]
	v_pk_mul_f32 v[14:15], v[14:15], v[148:149] op_sel_hi:[1,0]
	v_pk_mul_f32 v[12:13], v[12:13], v[148:149] op_sel_hi:[1,0]
	v_pk_mul_f32 v[10:11], v[10:11], v[148:149] op_sel_hi:[1,0]
	v_pk_mul_f32 v[8:9], v[8:9], v[148:149] op_sel_hi:[1,0]
	v_pk_mul_f32 v[6:7], v[6:7], v[148:149] op_sel_hi:[1,0]
	v_pk_mul_f32 v[4:5], v[4:5], v[148:149] op_sel_hi:[1,0]
	v_pk_mul_f32 v[2:3], v[2:3], v[148:149] op_sel_hi:[1,0]
	v_pk_mul_f32 v[0:1], v[0:1], v[148:149] op_sel_hi:[1,0]
	v_mul_f32_e32 v169, v169, v148
	v_pk_add_f32 v[52:53], v[52:53], v[152:153]
	v_pk_add_f32 v[148:149], v[154:155], v[156:157]
	v_mov_b32_e32 v167, v158
	v_pk_add_f32 v[52:53], v[52:53], v[148:149]
	v_cvt_pk_bf16_f32 v36, v36, v37
	v_cvt_pk_bf16_f32 v37, v38, v39
	v_cvt_pk_bf16_f32 v38, v40, v41
	v_cvt_pk_bf16_f32 v39, v42, v43
	v_cvt_pk_bf16_f32 v40, v54, v55
	s_nop 0
	v_add_f32_e32 v52, v52, v53
	v_cvt_pk_bf16_f32 v41, v58, v59
	v_cvt_pk_bf16_f32 v42, v62, v63
	v_cvt_pk_bf16_f32 v43, v66, v67
	v_cvt_pk_bf16_f32 v44, v44, v45
	v_cvt_pk_bf16_f32 v45, v46, v47
	v_cvt_pk_bf16_f32 v46, v48, v49
	v_cvt_pk_bf16_f32 v47, v50, v51
	v_cvt_pk_bf16_f32 v48, v56, v57
	v_cvt_pk_bf16_f32 v49, v60, v61
	v_cvt_pk_bf16_f32 v50, v64, v65
	v_cvt_pk_bf16_f32 v51, v150, v151
	s_branch .LBB0_789

.LBB0_797:
	v_exp_f32_e32 v148, v52
	s_nop 0
	v_exp_f32_e32 v150, v36
	v_exp_f32_e32 v149, v53
	v_exp_f32_e32 v151, v37
	v_exp_f32_e32 v54, v54
	v_exp_f32_e32 v152, v38
	v_exp_f32_e32 v55, v55
	v_exp_f32_e32 v153, v39
	v_exp_f32_e32 v38, v56
	v_exp_f32_e32 v56, v40
	v_exp_f32_e32 v39, v57
	v_exp_f32_e32 v57, v41
	v_exp_f32_e32 v40, v58
	v_exp_f32_e32 v58, v42
	v_exp_f32_e32 v41, v59
	v_exp_f32_e32 v59, v43
	v_exp_f32_e32 v42, v60
	v_exp_f32_e32 v60, v44
	v_exp_f32_e32 v43, v61
	v_exp_f32_e32 v61, v45
	v_exp_f32_e32 v44, v62
	v_exp_f32_e32 v62, v46
	v_exp_f32_e32 v45, v63
	v_exp_f32_e32 v63, v47
	v_exp_f32_e32 v46, v64
	v_exp_f32_e32 v64, v48
	v_exp_f32_e32 v47, v65
	v_exp_f32_e32 v65, v49
	v_exp_f32_e32 v48, v66
	v_exp_f32_e32 v66, v50
	v_exp_f32_e32 v49, v67
	v_exp_f32_e32 v67, v51
	v_pk_add_f32 v[36:37], v[38:39], v[148:149]
	v_pk_add_f32 v[50:51], v[40:41], v[54:55]
	v_pk_add_f32 v[52:53], v[56:57], v[150:151]
	v_pk_add_f32 v[154:155], v[58:59], v[152:153]
	v_pk_add_f32 v[36:37], v[42:43], v[36:37]
	v_pk_add_f32 v[50:51], v[44:45], v[50:51]
	v_pk_add_f32 v[52:53], v[60:61], v[52:53]
	v_pk_add_f32 v[154:155], v[62:63], v[154:155]
	v_pk_add_f32 v[36:37], v[46:47], v[36:37]
	v_pk_add_f32 v[50:51], v[48:49], v[50:51]
	v_pk_add_f32 v[52:53], v[64:65], v[52:53]
	v_pk_add_f32 v[154:155], v[66:67], v[154:155]
	v_pk_add_f32 v[36:37], v[36:37], v[50:51]
	v_pk_add_f32 v[50:51], v[52:53], v[154:155]
	s_xor_b64 s[16:17], s[16:17], -1
	v_pk_add_f32 v[36:37], v[50:51], v[36:37]
	s_andn2_b64 vcc, exec, s[16:17]
	v_add_f32_e32 v52, v36, v37
	s_mov_b64 s[42:43], -1
	v_cvt_pk_bf16_f32 v36, v148, v149
	v_cvt_pk_bf16_f32 v37, v54, v55
	v_cvt_pk_bf16_f32 v38, v38, v39
	v_cvt_pk_bf16_f32 v39, v40, v41
	v_cvt_pk_bf16_f32 v40, v42, v43
	v_cvt_pk_bf16_f32 v41, v44, v45
	v_cvt_pk_bf16_f32 v42, v46, v47
	v_cvt_pk_bf16_f32 v43, v48, v49
	v_cvt_pk_bf16_f32 v44, v150, v151
	v_cvt_pk_bf16_f32 v45, v152, v153
	v_cvt_pk_bf16_f32 v46, v56, v57
	v_cvt_pk_bf16_f32 v47, v58, v59
	v_cvt_pk_bf16_f32 v48, v60, v61
	v_cvt_pk_bf16_f32 v49, v62, v63
	v_cvt_pk_bf16_f32 v50, v64, v65
	v_cvt_pk_bf16_f32 v51, v66, v67
	s_cbranch_vccnz .LBB0_801
	v_cmp_ngt_f32_e32 vcc, s67, v52
	s_cbranch_vccz .LBB0_800
	ds_read_b128 v[52:55], v234 offset:19968
	ds_read_b128 v[36:39], v234 offset:13312
	ds_read_b128 v[148:151], v234 offset:13344
	ds_read_b128 v[152:155], v234 offset:20000
	s_waitcnt lgkmcnt(3)
	v_mfma_f32_32x32x16_bf16 v[52:67], v[52:55], v[68:71], 0
	s_waitcnt lgkmcnt(2)
	v_mfma_f32_32x32x16_bf16 v[36:51], v[36:39], v[68:71], 0
	s_waitcnt lgkmcnt(1)
	v_mfma_f32_32x32x16_bf16 v[36:51], v[148:151], v[72:75], v[36:51]
	s_waitcnt lgkmcnt(0)
	v_mfma_f32_32x32x16_bf16 v[52:67], v[152:155], v[72:75], v[52:67]
	ds_read_b128 v[148:151], v234 offset:13376
	ds_read_b128 v[152:155], v234 offset:20032
	s_waitcnt lgkmcnt(1)
	v_mfma_f32_32x32x16_bf16 v[36:51], v[148:151], v[76:79], v[36:51]
	s_waitcnt lgkmcnt(0)
	v_mfma_f32_32x32x16_bf16 v[52:67], v[152:155], v[76:79], v[52:67]
	ds_read_b128 v[148:151], v234 offset:13408
	ds_read_b128 v[152:155], v234 offset:20064
	s_waitcnt lgkmcnt(1)
	v_mfma_f32_32x32x16_bf16 v[36:51], v[148:151], v[80:83], v[36:51]
	s_waitcnt lgkmcnt(0)
	v_mfma_f32_32x32x16_bf16 v[52:67], v[152:155], v[80:83], v[52:67]
	ds_read_b128 v[148:151], v234 offset:13440
	ds_read_b128 v[152:155], v234 offset:20096
	s_waitcnt lgkmcnt(1)
	v_mfma_f32_32x32x16_bf16 v[36:51], v[148:151], v[84:87], v[36:51]
	s_waitcnt lgkmcnt(0)
	v_mfma_f32_32x32x16_bf16 v[52:67], v[152:155], v[84:87], v[52:67]
	ds_read_b128 v[148:151], v234 offset:13472
	ds_read_b128 v[152:155], v234 offset:20128
	s_waitcnt lgkmcnt(1)
	v_mfma_f32_32x32x16_bf16 v[36:51], v[148:151], v[88:91], v[36:51]
	v_max3_f32 v148, v36, v37, v38
	s_nop 0
	v_max3_f32 v148, v148, v39, v40
	s_nop 0
	v_max3_f32 v148, v148, v41, v42
	s_nop 9
	v_max_f32_e32 v151, v51, v51
	s_waitcnt lgkmcnt(0)
	v_mfma_f32_32x32x16_bf16 v[52:67], v[152:155], v[88:91], v[52:67]
	v_max3_f32 v149, v52, v53, v54
	v_max3_f32 v148, v148, v43, v44
	s_nop 0
	v_max3_f32 v149, v149, v55, v56
	v_max3_f32 v148, v148, v45, v46
	s_nop 10
	v_max_f32_e32 v150, v67, v67
	v_max3_f32 v149, v149, v57, v58
	v_max3_f32 v148, v148, v47, v48
	v_max_f32_e32 v150, v151, v150
	v_max3_f32 v149, v149, v59, v60
	v_max3_f32 v148, v148, v49, v50
	s_nop 0
	v_max3_f32 v149, v149, v61, v62
	s_nop 0
	v_max3_f32 v149, v149, v63, v64
	s_nop 0
	v_max3_f32 v149, v149, v65, v66
	s_nop 0
	v_max3_f32 v148, v148, v149, v150
	s_nop 0
	v_mov_b32_e32 v149, v148
	s_nop 1
	v_permlane32_swap_b32_e32 v148, v149
	v_max3_f32 v158, v167, v148, v149
	v_sub_f32_e32 v36, v36, v158
	v_sub_f32_e32 v52, v52, v158
	v_sub_f32_e32 v37, v37, v158
	v_sub_f32_e32 v53, v53, v158
	v_sub_f32_e32 v38, v38, v158
	v_sub_f32_e32 v54, v54, v158
	v_sub_f32_e32 v39, v39, v158
	v_sub_f32_e32 v55, v55, v158
	v_sub_f32_e32 v40, v40, v158
	v_sub_f32_e32 v56, v56, v158
	v_sub_f32_e32 v41, v41, v158
	v_sub_f32_e32 v57, v57, v158
	v_sub_f32_e32 v42, v42, v158
	v_sub_f32_e32 v58, v58, v158
	v_sub_f32_e32 v43, v43, v158
	v_sub_f32_e32 v59, v59, v158
	v_sub_f32_e32 v149, v44, v158
	v_sub_f32_e32 v150, v45, v158
	v_sub_f32_e32 v151, v46, v158
	v_sub_f32_e32 v152, v47, v158
	v_exp_f32_e32 v36, v36
	v_exp_f32_e32 v44, v52
	v_exp_f32_e32 v37, v37
	v_exp_f32_e32 v45, v53
	v_exp_f32_e32 v38, v38
	v_exp_f32_e32 v46, v54
	v_exp_f32_e32 v39, v39
	v_exp_f32_e32 v47, v55
	v_sub_f32_e32 v60, v60, v158
	v_sub_f32_e32 v61, v61, v158
	v_sub_f32_e32 v62, v62, v158
	v_sub_f32_e32 v63, v63, v158
	v_sub_f32_e32 v153, v48, v158
	v_sub_f32_e32 v154, v49, v158
	v_sub_f32_e32 v155, v50, v158
	v_sub_f32_e32 v157, v51, v158
	v_exp_f32_e32 v40, v40
	v_exp_f32_e32 v48, v56
	v_exp_f32_e32 v41, v41
	v_exp_f32_e32 v49, v57
	v_exp_f32_e32 v42, v42
	v_exp_f32_e32 v50, v58
	v_exp_f32_e32 v43, v43
	v_exp_f32_e32 v51, v59
	v_sub_f32_e32 v64, v64, v158
	v_sub_f32_e32 v65, v65, v158
	v_sub_f32_e32 v156, v66, v158
	v_sub_f32_e32 v159, v67, v158
	v_exp_f32_e32 v54, v149
	v_exp_f32_e32 v56, v60
	v_exp_f32_e32 v55, v150
	v_exp_f32_e32 v57, v61
	v_exp_f32_e32 v58, v151
	v_exp_f32_e32 v60, v62
	v_exp_f32_e32 v59, v152
	v_exp_f32_e32 v61, v63
	v_sub_f32_e32 v148, v167, v158
	v_exp_f32_e32 v62, v153
	v_exp_f32_e32 v64, v64
	v_exp_f32_e32 v63, v154
	v_exp_f32_e32 v65, v65
	v_exp_f32_e32 v66, v155
	v_exp_f32_e32 v150, v156
	v_exp_f32_e32 v67, v157
	v_exp_f32_e32 v151, v159
	v_exp_f32_e32 v148, v148
	v_pk_add_f32 v[52:53], v[36:37], 0 op_sel_hi:[1,0]
	v_pk_add_f32 v[152:153], v[38:39], 0 op_sel_hi:[1,0]
	v_pk_add_f32 v[154:155], v[44:45], 0 op_sel_hi:[1,0]
	v_pk_add_f32 v[156:157], v[46:47], 0 op_sel_hi:[1,0]
	v_pk_add_f32 v[52:53], v[40:41], v[52:53]
	v_pk_add_f32 v[152:153], v[42:43], v[152:153]
	v_pk_add_f32 v[154:155], v[48:49], v[154:155]
	v_pk_add_f32 v[156:157], v[50:51], v[156:157]
	v_pk_add_f32 v[52:53], v[54:55], v[52:53]
	v_pk_add_f32 v[152:153], v[58:59], v[152:153]
	v_pk_add_f32 v[154:155], v[56:57], v[154:155]
	v_pk_add_f32 v[156:157], v[60:61], v[156:157]
	v_pk_add_f32 v[52:53], v[62:63], v[52:53]
	v_pk_add_f32 v[152:153], v[66:67], v[152:153]
	v_pk_add_f32 v[154:155], v[64:65], v[154:155]
	v_pk_add_f32 v[156:157], v[150:151], v[156:157]
	v_pk_mul_f32 v[34:35], v[34:35], v[148:149] op_sel_hi:[1,0]
	v_pk_mul_f32 v[32:33], v[32:33], v[148:149] op_sel_hi:[1,0]
	v_pk_mul_f32 v[30:31], v[30:31], v[148:149] op_sel_hi:[1,0]
	v_pk_mul_f32 v[28:29], v[28:29], v[148:149] op_sel_hi:[1,0]
	v_pk_mul_f32 v[26:27], v[26:27], v[148:149] op_sel_hi:[1,0]
	v_pk_mul_f32 v[24:25], v[24:25], v[148:149] op_sel_hi:[1,0]
	v_pk_mul_f32 v[22:23], v[22:23], v[148:149] op_sel_hi:[1,0]
	v_pk_mul_f32 v[20:21], v[20:21], v[148:149] op_sel_hi:[1,0]
	v_pk_mul_f32 v[14:15], v[14:15], v[148:149] op_sel_hi:[1,0]
	v_pk_mul_f32 v[12:13], v[12:13], v[148:149] op_sel_hi:[1,0]
	v_pk_mul_f32 v[10:11], v[10:11], v[148:149] op_sel_hi:[1,0]
	v_pk_mul_f32 v[8:9], v[8:9], v[148:149] op_sel_hi:[1,0]
	v_pk_mul_f32 v[6:7], v[6:7], v[148:149] op_sel_hi:[1,0]
	v_pk_mul_f32 v[4:5], v[4:5], v[148:149] op_sel_hi:[1,0]
	v_pk_mul_f32 v[2:3], v[2:3], v[148:149] op_sel_hi:[1,0]
	v_pk_mul_f32 v[0:1], v[0:1], v[148:149] op_sel_hi:[1,0]
	v_mul_f32_e32 v169, v169, v148
	v_pk_add_f32 v[52:53], v[52:53], v[152:153]
	v_pk_add_f32 v[148:149], v[154:155], v[156:157]
	v_mov_b32_e32 v167, v158
	v_pk_add_f32 v[52:53], v[52:53], v[148:149]
	v_cvt_pk_bf16_f32 v36, v36, v37
	v_cvt_pk_bf16_f32 v37, v38, v39
	v_cvt_pk_bf16_f32 v38, v40, v41
	v_cvt_pk_bf16_f32 v39, v42, v43
	v_cvt_pk_bf16_f32 v40, v54, v55
	s_nop 0
	v_add_f32_e32 v52, v52, v53
	v_cvt_pk_bf16_f32 v41, v58, v59
	v_cvt_pk_bf16_f32 v42, v62, v63
	v_cvt_pk_bf16_f32 v43, v66, v67
	v_cvt_pk_bf16_f32 v44, v44, v45
	v_cvt_pk_bf16_f32 v45, v46, v47
	v_cvt_pk_bf16_f32 v46, v48, v49
	v_cvt_pk_bf16_f32 v47, v50, v51
	v_cvt_pk_bf16_f32 v48, v56, v57
	v_cvt_pk_bf16_f32 v49, v60, v61
	v_cvt_pk_bf16_f32 v50, v64, v65
	v_cvt_pk_bf16_f32 v51, v150, v151
	s_branch .LBB0_801
